# v30: GEMM3a mid-K scaling: all 16 ratio-tile loads of both 128-row halves issued before the first wait (one exposed round trip instead of two)
# speedup vs baseline: 1.0026x; 1.0026x over previous
; #define PG8_STAGE(bufoff, gbase, voff) do { _Pragma("unroll") for (int _i = 0; _i < 2; ++_i) \
;         __builtin_amdgcn_global_load_lds((const unsigned*)((const char*)(gbase) + (voff)[_i]), (LAS unsigned*)(lds + (bufoff) + ldsw + _i * 8192), 16, 0, 0); } while (0)
; #define PG8_LDA(dst, b, h) do { _Pragma("unroll") for (int m = 0; m < 4; ++m) _Pragma("unroll") for (int k = 0; k < 2; ++k) dst[m][k] = *(const LAS bf16x8*)(lds + PG8_SA(b, h) + aoff + m * 2048 + k * 1024); } while (0)
; #define PG8_LDB(dst, b, h) do { _Pragma("unroll") for (int n = 0; n < 2; ++n) _Pragma("unroll") for (int k = 0; k < 2; ++k) dst[n][k] = *(const LAS bf16x8*)(lds + PG8_SB(b, h) + boff + n * 2048 + k * 1024); } while (0)
; #define PG8_MMA(ai, bj, At, Bt) do { __builtin_amdgcn_s_setprio(1); _Pragma("unroll") for (int m = 0; m < 4; ++m) _Pragma("unroll") for (int n = 0; n < 2; ++n) _Pragma("unroll") for (int k = 0; k < 2; ++k) \
;         acc[ai][bj][m][n] = __builtin_amdgcn_mfma_f32_16x16x32_bf16(Bt[n][k], At[m][k], acc[ai][bj][m][n], 0, 0, 0); __builtin_amdgcn_s_setprio(0); } while (0)
; #define PG8_WAIT_V(n) asm volatile("s_waitcnt vmcnt(" #n ")" ::: "memory")
; #define PG8_WAIT_L(n) asm volatile("s_waitcnt lgkmcnt(" #n ")" ::: "memory")
; template <class Epi>
; __device__ __forceinline__ void gemm_phase(LAS unsigned char* lds, const Gemm g, const StaticOrder& S, const Epi& E) {
;     ...
;         for (int t = hf * nth; t < (hf + 1) * nth; t += 2) {
;             const bool last = (t == nt - 2);
;             const char* a1 = cA + (size_t)(t + 1) * kstep;
;             const char* a2 = last ? nA : cA + (size_t)(t + 2) * kstep; const char* b2 = last ? nB : cB + (size_t)(t + 2) * kstep;
;             const char* a3 = a2 + kstep; const char* b3 = b2 + kstep;
;             PG8_LDB(B0, 0, 0); PG8_LDB(B1, 0, 1); PG8_SCHED; PG8_LDA(At, 0, 0); PG8_STAGE(PG8_SA(1, 1), a1 + hstepA, voffA);
;             PG8_WAIT_V(8); PG8_WAIT_L(0); PG8_BAR; PG8_MMA(0, 0, At, B0); PG8_MMA(0, 1, At, B1); PG8_BAR; PG8_SCHED;
;             PG8_LDA(At, 0, 1); PG8_STAGE(PG8_SB(0, 0), b2, voffB); PG8_STAGE(PG8_SB(0, 1), b2 + hstepB, voffB); PG8_STAGE(PG8_SA(0, 0), a2, voffA);
;             PG8_WAIT_V(8); PG8_WAIT_L(0); PG8_BAR; PG8_MMA(1, 0, At, B0); PG8_MMA(1, 1, At, B1); PG8_BAR; PG8_SCHED;
;             PG8_LDB(B0, 1, 0); PG8_LDB(B1, 1, 1); PG8_SCHED; PG8_LDA(At, 1, 0); PG8_STAGE(PG8_SA(0, 1), a2 + hstepA, voffA);
.LBB0_785:
	v_add_u32_e32 v0, s63, v196
	ds_read_b128 v[134:137], v0
	ds_read_b128 v[138:141], v0 offset:1024
	ds_read_b128 v[142:145], v0 offset:2048
	ds_read_b128 v[146:149], v0 offset:3072
	v_add_u32_e32 v0, s64, v196
	ds_read_b128 v[150:153], v0
	ds_read_b128 v[154:157], v0 offset:1024
	ds_read_b128 v[158:161], v0 offset:2048
	ds_read_b128 v[162:165], v0 offset:3072
	s_add_i32 s8, s8, 2
	s_add_u32 s42, s50, s36
	s_addc_u32 s43, s51, s37
	s_add_u32 s52, s48, s36
	s_addc_u32 s53, s49, s37
	s_cmp_eq_u32 s36, s46
	s_cselect_b32 s43, s21, s43
	s_cselect_b32 s42, s75, s42
	s_cselect_b32 s53, s19, s53
	s_cselect_b32 s52, s76, s52
	v_lshl_add_u64 v[170:171], v[132:133], 0, s[36:37]
	s_add_i32 m0, s55, 0xc000
	ds_read_b128 v[166:169], v198
	ds_read_b128 v[200:203], v198 offset:1024
	ds_read_b128 v[204:207], v198 offset:2048
	ds_read_b128 v[208:211], v198 offset:3072
	ds_read_b128 v[212:215], v198 offset:4096
	ds_read_b128 v[216:219], v198 offset:5120
	ds_read_b128 v[220:223], v198 offset:6144
	ds_read_b128 v[224:227], v198 offset:7168
	global_load_lds_dwordx4 v[170:171], off
	v_lshl_add_u64 v[170:171], v[2:3], 0, s[36:37]
	s_add_i32 m0, s55, 0xe000
	s_nop 0
	global_load_lds_dwordx4 v[170:171], off
	s_waitcnt vmcnt(8)
	s_waitcnt lgkmcnt(0)
	s_barrier
	s_setprio 1
	s_waitcnt lgkmcnt(0)
	v_mfma_f32_16x16x32_bf16 v[128:131], v[134:137], v[166:169], v[128:131]
	v_mfma_f32_16x16x32_bf16 v[124:127], v[142:145], v[166:169], v[124:127]
	v_mfma_f32_16x16x32_bf16 v[112:115], v[134:137], v[204:207], v[112:115]
	v_mfma_f32_16x16x32_bf16 v[108:111], v[142:145], v[204:207], v[108:111]
	v_mfma_f32_16x16x32_bf16 v[96:99], v[134:137], v[212:215], v[96:99]
	v_mfma_f32_16x16x32_bf16 v[92:95], v[142:145], v[212:215], v[92:95]
	v_mfma_f32_16x16x32_bf16 v[80:83], v[134:137], v[220:223], v[80:83]
	v_mfma_f32_16x16x32_bf16 v[76:79], v[142:145], v[220:223], v[76:79]
	v_mfma_f32_16x16x32_bf16 v[128:131], v[138:141], v[200:203], v[128:131]
	v_mfma_f32_16x16x32_bf16 v[124:127], v[146:149], v[200:203], v[124:127]
	v_mfma_f32_16x16x32_bf16 v[112:115], v[138:141], v[208:211], v[112:115]
	v_mfma_f32_16x16x32_bf16 v[108:111], v[146:149], v[208:211], v[108:111]
	v_mfma_f32_16x16x32_bf16 v[96:99], v[138:141], v[216:219], v[96:99]
	v_mfma_f32_16x16x32_bf16 v[92:95], v[146:149], v[216:219], v[92:95]
	v_mfma_f32_16x16x32_bf16 v[80:83], v[138:141], v[224:227], v[80:83]
	v_mfma_f32_16x16x32_bf16 v[76:79], v[146:149], v[224:227], v[76:79]
	s_setprio 0
	s_setprio 1
	v_mfma_f32_16x16x32_bf16 v[120:123], v[150:153], v[166:169], v[120:123]
	v_mfma_f32_16x16x32_bf16 v[116:119], v[158:161], v[166:169], v[116:119]
	v_mfma_f32_16x16x32_bf16 v[104:107], v[150:153], v[204:207], v[104:107]
	v_mfma_f32_16x16x32_bf16 v[100:103], v[158:161], v[204:207], v[100:103]
	v_mfma_f32_16x16x32_bf16 v[88:91], v[150:153], v[212:215], v[88:91]
	v_mfma_f32_16x16x32_bf16 v[84:87], v[158:161], v[212:215], v[84:87]
	v_mfma_f32_16x16x32_bf16 v[72:75], v[150:153], v[220:223], v[72:75]
	v_mfma_f32_16x16x32_bf16 v[68:71], v[158:161], v[220:223], v[68:71]
	v_mfma_f32_16x16x32_bf16 v[120:123], v[154:157], v[200:203], v[120:123]
	v_mfma_f32_16x16x32_bf16 v[116:119], v[162:165], v[200:203], v[116:119]
	v_mfma_f32_16x16x32_bf16 v[104:107], v[154:157], v[208:211], v[104:107]
	v_mfma_f32_16x16x32_bf16 v[100:103], v[162:165], v[208:211], v[100:103]
	v_mfma_f32_16x16x32_bf16 v[88:91], v[154:157], v[216:219], v[88:91]
	v_mfma_f32_16x16x32_bf16 v[84:87], v[162:165], v[216:219], v[84:87]
	v_mfma_f32_16x16x32_bf16 v[72:75], v[154:157], v[224:227], v[72:75]
	v_mfma_f32_16x16x32_bf16 v[68:71], v[162:165], v[224:227], v[68:71]
	s_setprio 0
	s_barrier
	s_add_i32 s78, s63, s54
	v_lshl_add_u64 v[170:171], s[52:53], 0, v[174:175]
	s_mov_b32 m0, s78
	ds_read_b128 v[166:169], v198 offset:16384
	ds_read_b128 v[200:203], v198 offset:17408
	ds_read_b128 v[204:207], v198 offset:18432
	ds_read_b128 v[208:211], v198 offset:19456
	ds_read_b128 v[212:215], v198 offset:20480
	ds_read_b128 v[216:219], v198 offset:21504
	ds_read_b128 v[220:223], v198 offset:22528
	ds_read_b128 v[224:227], v198 offset:23552
	global_load_lds_dwordx4 v[170:171], off
	s_add_i32 m0, s78, 0x2000
	s_add_u32 s78, s52, 0x80000
	v_lshl_add_u64 v[228:229], s[52:53], 0, v[178:179]
	s_addc_u32 s79, s53, 0
	s_add_i32 s80, s64, s54
	global_load_lds_dwordx4 v[228:229], off
	v_lshl_add_u64 v[230:231], s[78:79], 0, v[174:175]
	s_mov_b32 m0, s80
	v_lshl_add_u64 v[232:233], s[42:43], 0, v[176:177]
	global_load_lds_dwordx4 v[230:231], off
	v_lshl_add_u64 v[230:231], s[78:79], 0, v[178:179]
	s_add_i32 m0, s80, 0x2000
	s_nop 0
	global_load_lds_dwordx4 v[230:231], off
	v_lshl_add_u64 v[230:231], s[42:43], 0, v[172:173]
	s_mov_b32 m0, s55
	s_nop 0
	global_load_lds_dwordx4 v[230:231], off
	s_mov_b32 m0, s56
	s_nop 0
	global_load_lds_dwordx4 v[232:233], off
	s_waitcnt vmcnt(8)
	s_waitcnt lgkmcnt(0)
	s_barrier
; #define PG8_STAGE(bufoff, gbase, voff) do { _Pragma("unroll") for (int _i = 0; _i < 2; ++_i) \
;         __builtin_amdgcn_global_load_lds((const unsigned*)((const char*)(gbase) + (voff)[_i]), (LAS unsigned*)(lds + (bufoff) + ldsw + _i * 8192), 16, 0, 0); } while (0)
; #define PG8_LDA(dst, b, h) do { _Pragma("unroll") for (int m = 0; m < 4; ++m) _Pragma("unroll") for (int k = 0; k < 2; ++k) dst[m][k] = *(const LAS bf16x8*)(lds + PG8_SA(b, h) + aoff + m * 2048 + k * 1024); } while (0)
; #define PG8_LDB(dst, b, h) do { _Pragma("unroll") for (int n = 0; n < 2; ++n) _Pragma("unroll") for (int k = 0; k < 2; ++k) dst[n][k] = *(const LAS bf16x8*)(lds + PG8_SB(b, h) + boff + n * 2048 + k * 1024); } while (0)
; #define PG8_MMA(ai, bj, At, Bt) do { __builtin_amdgcn_s_setprio(1); _Pragma("unroll") for (int m = 0; m < 4; ++m) _Pragma("unroll") for (int n = 0; n < 2; ++n) _Pragma("unroll") for (int k = 0; k < 2; ++k) \
;         acc[ai][bj][m][n] = __builtin_amdgcn_mfma_f32_16x16x32_bf16(Bt[n][k], At[m][k], acc[ai][bj][m][n], 0, 0, 0); __builtin_amdgcn_s_setprio(0); } while (0)
; #define PG8_WAIT_V(n) asm volatile("s_waitcnt vmcnt(" #n ")" ::: "memory")
; #define PG8_WAIT_L(n) asm volatile("s_waitcnt lgkmcnt(" #n ")" ::: "memory")
; #define PG8_BAR __builtin_amdgcn_s_barrier()
; #define PG8_SCHED __builtin_amdgcn_sched_barrier(0)
; template <class Epi>
; __device__ __forceinline__ void gemm_phase(LAS unsigned char* lds, const Gemm g, const StaticOrder& S, const Epi& E) {
;     ...
;             PG8_WAIT_V(8); PG8_WAIT_L(0); PG8_BAR; PG8_MMA(0, 0, At, B0); PG8_MMA(0, 1, At, B1); PG8_BAR; PG8_SCHED;
;             PG8_LDA(At, 0, 1); PG8_STAGE(PG8_SB(0, 0), b2, voffB); PG8_STAGE(PG8_SB(0, 1), b2 + hstepB, voffB); PG8_STAGE(PG8_SA(0, 0), a2, voffA);
;             PG8_WAIT_V(8); PG8_WAIT_L(0); PG8_BAR; PG8_MMA(1, 0, At, B0); PG8_MMA(1, 1, At, B1); PG8_BAR; PG8_SCHED;
;             PG8_LDB(B0, 1, 0); PG8_LDB(B1, 1, 1); PG8_SCHED; PG8_LDA(At, 1, 0); PG8_STAGE(PG8_SA(0, 1), a2 + hstepA, voffA);
;             PG8_WAIT_V(8); PG8_WAIT_L(0); PG8_BAR; PG8_MMA(0, 0, At, B0); PG8_MMA(0, 1, At, B1); PG8_BAR; PG8_SCHED;
;             PG8_LDA(At, 1, 1); PG8_STAGE(PG8_SB(1, 0), b3, voffB); PG8_STAGE(PG8_SB(1, 1), b3 + hstepB, voffB); PG8_STAGE(PG8_SA(1, 0), a3, voffA);
;             PG8_WAIT_V(8); PG8_WAIT_L(0); PG8_BAR; PG8_MMA(1, 0, At, B0); PG8_MMA(1, 1, At, B1); PG8_BAR; PG8_SCHED;
	s_setprio 1
	s_waitcnt lgkmcnt(0)
	v_mfma_f32_16x16x32_bf16 v[64:67], v[134:137], v[166:169], v[64:67]
	v_mfma_f32_16x16x32_bf16 v[60:63], v[142:145], v[166:169], v[60:63]
	v_mfma_f32_16x16x32_bf16 v[48:51], v[134:137], v[204:207], v[48:51]
	v_mfma_f32_16x16x32_bf16 v[44:47], v[142:145], v[204:207], v[44:47]
	v_mfma_f32_16x16x32_bf16 v[32:35], v[134:137], v[212:215], v[32:35]
	v_mfma_f32_16x16x32_bf16 v[28:31], v[142:145], v[212:215], v[28:31]
	v_mfma_f32_16x16x32_bf16 v[16:19], v[134:137], v[220:223], v[16:19]
	v_mfma_f32_16x16x32_bf16 v[12:15], v[142:145], v[220:223], v[12:15]
	v_mfma_f32_16x16x32_bf16 v[64:67], v[138:141], v[200:203], v[64:67]
	v_mfma_f32_16x16x32_bf16 v[60:63], v[146:149], v[200:203], v[60:63]
	v_mfma_f32_16x16x32_bf16 v[48:51], v[138:141], v[208:211], v[48:51]
	v_mfma_f32_16x16x32_bf16 v[44:47], v[146:149], v[208:211], v[44:47]
	v_mfma_f32_16x16x32_bf16 v[32:35], v[138:141], v[216:219], v[32:35]
	v_mfma_f32_16x16x32_bf16 v[28:31], v[146:149], v[216:219], v[28:31]
	v_mfma_f32_16x16x32_bf16 v[16:19], v[138:141], v[224:227], v[16:19]
	v_mfma_f32_16x16x32_bf16 v[12:15], v[146:149], v[224:227], v[12:15]
	s_setprio 0
	s_setprio 1
	v_mfma_f32_16x16x32_bf16 v[56:59], v[150:153], v[166:169], v[56:59]
	v_mfma_f32_16x16x32_bf16 v[52:55], v[158:161], v[166:169], v[52:55]
	v_mfma_f32_16x16x32_bf16 v[40:43], v[150:153], v[204:207], v[40:43]
	v_mfma_f32_16x16x32_bf16 v[36:39], v[158:161], v[204:207], v[36:39]
	v_mfma_f32_16x16x32_bf16 v[24:27], v[150:153], v[212:215], v[24:27]
	v_mfma_f32_16x16x32_bf16 v[20:23], v[158:161], v[212:215], v[20:23]
	v_mfma_f32_16x16x32_bf16 v[8:11], v[150:153], v[220:223], v[8:11]
	v_mfma_f32_16x16x32_bf16 v[4:7], v[158:161], v[220:223], v[4:7]
	v_mfma_f32_16x16x32_bf16 v[56:59], v[154:157], v[200:203], v[56:59]
	v_mfma_f32_16x16x32_bf16 v[52:55], v[162:165], v[200:203], v[52:55]
	v_mfma_f32_16x16x32_bf16 v[40:43], v[154:157], v[208:211], v[40:43]
	v_mfma_f32_16x16x32_bf16 v[36:39], v[162:165], v[208:211], v[36:39]
	v_mfma_f32_16x16x32_bf16 v[24:27], v[154:157], v[216:219], v[24:27]
	v_mfma_f32_16x16x32_bf16 v[20:23], v[162:165], v[216:219], v[20:23]
	v_mfma_f32_16x16x32_bf16 v[8:11], v[154:157], v[224:227], v[8:11]
	v_mfma_f32_16x16x32_bf16 v[4:7], v[162:165], v[224:227], v[4:7]
	s_setprio 0
	s_barrier
	s_add_i32 s78, 0, 0x18000
	v_add_u32_e32 v0, s78, v196
	s_add_i32 s79, 0, 0x1c000
	ds_read_b128 v[134:137], v0
	ds_read_b128 v[138:141], v0 offset:1024
	ds_read_b128 v[142:145], v0 offset:2048
	ds_read_b128 v[146:149], v0 offset:3072
	v_add_u32_e32 v0, s79, v196
	ds_read_b128 v[150:153], v0
	ds_read_b128 v[154:157], v0 offset:1024
	ds_read_b128 v[158:161], v0 offset:2048
	ds_read_b128 v[162:165], v0 offset:3072
	s_add_u32 s42, s42, 0x80000
	s_addc_u32 s43, s43, 0
	s_mov_b32 m0, s57
	v_lshl_add_u64 v[234:235], s[42:43], 0, v[172:173]
	ds_read_b128 v[166:169], v198 offset:32768
	ds_read_b128 v[200:203], v198 offset:33792
	ds_read_b128 v[204:207], v198 offset:34816
	ds_read_b128 v[208:211], v198 offset:35840
	ds_read_b128 v[212:215], v198 offset:36864
	ds_read_b128 v[216:219], v198 offset:37888
	ds_read_b128 v[220:223], v198 offset:38912
	ds_read_b128 v[224:227], v198 offset:39936
	global_load_lds_dwordx4 v[234:235], off
	v_lshl_add_u64 v[234:235], s[42:43], 0, v[176:177]
	s_mov_b32 m0, s58
	s_nop 0
	global_load_lds_dwordx4 v[234:235], off
	s_waitcnt vmcnt(8)
	s_waitcnt lgkmcnt(0)
	s_barrier
	s_setprio 1
	s_waitcnt lgkmcnt(0)
	v_mfma_f32_16x16x32_bf16 v[128:131], v[134:137], v[166:169], v[128:131]
	v_mfma_f32_16x16x32_bf16 v[124:127], v[142:145], v[166:169], v[124:127]
	v_mfma_f32_16x16x32_bf16 v[112:115], v[134:137], v[204:207], v[112:115]
	v_mfma_f32_16x16x32_bf16 v[108:111], v[142:145], v[204:207], v[108:111]
	v_mfma_f32_16x16x32_bf16 v[96:99], v[134:137], v[212:215], v[96:99]
	v_mfma_f32_16x16x32_bf16 v[92:95], v[142:145], v[212:215], v[92:95]
	v_mfma_f32_16x16x32_bf16 v[80:83], v[134:137], v[220:223], v[80:83]
	v_mfma_f32_16x16x32_bf16 v[76:79], v[142:145], v[220:223], v[76:79]
	v_mfma_f32_16x16x32_bf16 v[128:131], v[138:141], v[200:203], v[128:131]
	v_mfma_f32_16x16x32_bf16 v[124:127], v[146:149], v[200:203], v[124:127]
	v_mfma_f32_16x16x32_bf16 v[112:115], v[138:141], v[208:211], v[112:115]
	v_mfma_f32_16x16x32_bf16 v[108:111], v[146:149], v[208:211], v[108:111]
	v_mfma_f32_16x16x32_bf16 v[96:99], v[138:141], v[216:219], v[96:99]
	v_mfma_f32_16x16x32_bf16 v[92:95], v[146:149], v[216:219], v[92:95]
	v_mfma_f32_16x16x32_bf16 v[80:83], v[138:141], v[224:227], v[80:83]
	v_mfma_f32_16x16x32_bf16 v[76:79], v[146:149], v[224:227], v[76:79]
	s_setprio 0
	s_setprio 1
	v_mfma_f32_16x16x32_bf16 v[120:123], v[150:153], v[166:169], v[120:123]
	v_mfma_f32_16x16x32_bf16 v[116:119], v[158:161], v[166:169], v[116:119]
	v_mfma_f32_16x16x32_bf16 v[104:107], v[150:153], v[204:207], v[104:107]
	v_mfma_f32_16x16x32_bf16 v[100:103], v[158:161], v[204:207], v[100:103]
	v_mfma_f32_16x16x32_bf16 v[88:91], v[150:153], v[212:215], v[88:91]
	v_mfma_f32_16x16x32_bf16 v[84:87], v[158:161], v[212:215], v[84:87]
	v_mfma_f32_16x16x32_bf16 v[72:75], v[150:153], v[220:223], v[72:75]
	v_mfma_f32_16x16x32_bf16 v[68:71], v[158:161], v[220:223], v[68:71]
	v_mfma_f32_16x16x32_bf16 v[120:123], v[154:157], v[200:203], v[120:123]
	v_mfma_f32_16x16x32_bf16 v[116:119], v[162:165], v[200:203], v[116:119]
	v_mfma_f32_16x16x32_bf16 v[104:107], v[154:157], v[208:211], v[104:107]
	v_mfma_f32_16x16x32_bf16 v[100:103], v[162:165], v[208:211], v[100:103]
	v_mfma_f32_16x16x32_bf16 v[88:91], v[154:157], v[216:219], v[88:91]
	v_mfma_f32_16x16x32_bf16 v[84:87], v[162:165], v[216:219], v[84:87]
	v_mfma_f32_16x16x32_bf16 v[72:75], v[154:157], v[224:227], v[72:75]
	v_mfma_f32_16x16x32_bf16 v[68:71], v[162:165], v[224:227], v[68:71]
	s_setprio 0
	s_barrier
; #define PG8_STAGE(bufoff, gbase, voff) do { _Pragma("unroll") for (int _i = 0; _i < 2; ++_i) \
;         __builtin_amdgcn_global_load_lds((const unsigned*)((const char*)(gbase) + (voff)[_i]), (LAS unsigned*)(lds + (bufoff) + ldsw + _i * 8192), 16, 0, 0); } while (0)
; #define PG8_WAIT_V(n) asm volatile("s_waitcnt vmcnt(" #n ")" ::: "memory")
; template <class Epi>
; __device__ __forceinline__ void gemm_phase(LAS unsigned char* lds, const Gemm g, const StaticOrder& S, const Epi& E) {
;     ...
;             PG8_LDB(B0, 0, 0); PG8_LDB(B1, 0, 1); PG8_SCHED; PG8_LDA(At, 0, 0); PG8_STAGE(PG8_SA(1, 1), a1 + hstepA, voffA);
;             PG8_WAIT_V(8); PG8_WAIT_L(0); PG8_BAR; PG8_MMA(0, 0, At, B0); PG8_MMA(0, 1, At, B1); PG8_BAR; PG8_SCHED;
;             PG8_LDA(At, 0, 1); PG8_STAGE(PG8_SB(0, 0), b2, voffB); PG8_STAGE(PG8_SB(0, 1), b2 + hstepB, voffB); PG8_STAGE(PG8_SA(0, 0), a2, voffA);
;             PG8_WAIT_V(8); PG8_WAIT_L(0); PG8_BAR; PG8_MMA(1, 0, At, B0); PG8_MMA(1, 1, At, B1); PG8_BAR; PG8_SCHED;
;             PG8_LDB(B0, 1, 0); PG8_LDB(B1, 1, 1); PG8_SCHED; PG8_LDA(At, 1, 0); PG8_STAGE(PG8_SA(0, 1), a2 + hstepA, voffA);
;             PG8_WAIT_V(8); PG8_WAIT_L(0); PG8_BAR; PG8_MMA(0, 0, At, B0); PG8_MMA(0, 1, At, B1); PG8_BAR; PG8_SCHED;
;             PG8_LDA(At, 1, 1); PG8_STAGE(PG8_SB(1, 0), b3, voffB); PG8_STAGE(PG8_SB(1, 1), b3 + hstepB, voffB); PG8_STAGE(PG8_SA(1, 0), a3, voffA);
;             PG8_WAIT_V(8); PG8_WAIT_L(0); PG8_BAR; PG8_MMA(1, 0, At, B0); PG8_MMA(1, 1, At, B1); PG8_BAR; PG8_SCHED;
;         }
;         if constexpr (Epi::MID) { if (hf == 0) E.mid(acc, cur, wr, wc, fr, fq); }
;     __device__ __forceinline__ void mid(f32x4 (&acc)[2][2][4][2], const pg8::Unit& u, int wr, int wc, int fr, int fq) const {
;         const int row0 = u.pm * 256 + wr * 64 + fr, col0 = u.pn * 256 + wc * 32 + 8 * fq;
;         unsigned boff = (unsigned)row0 * 2048u + (unsigned)col0 * 2u; asm volatile("" : "+v"(boff));
; #pragma unroll
;         for (int ai = 0; ai < 2; ++ai) {
;             u32x4 ga[4][2];
; #pragma unroll
;             for (int m = 0; m < 4; ++m) { const bf16_t* rowp = (const bf16_t*)((const char*)PJ + (size_t)(boff + (unsigned)((ai * 128 + m * 16) * 2048)));
; #pragma unroll
;                 for (int bj = 0; bj < 2; ++bj) ga[m][bj] = *(const u32x4*)(rowp + T_GA + bj * 128); }
;             __builtin_amdgcn_sched_barrier(0);
	s_add_i32 s42, s78, s54
	v_lshl_add_u64 v[170:171], v[170:171], 0, s[12:13]
	s_mov_b32 m0, s42
	ds_read_b128 v[166:169], v198 offset:49152
	ds_read_b128 v[200:203], v198 offset:50176
	ds_read_b128 v[204:207], v198 offset:51200
	ds_read_b128 v[208:211], v198 offset:52224
	ds_read_b128 v[212:215], v198 offset:53248
	ds_read_b128 v[216:219], v198 offset:54272
	ds_read_b128 v[220:223], v198 offset:55296
	ds_read_b128 v[224:227], v198 offset:56320
	global_load_lds_dwordx4 v[170:171], off
	s_add_i32 m0, s42, 0x2000
	s_add_u32 s42, s52, 0x80080
	v_lshl_add_u64 v[170:171], v[228:229], 0, s[12:13]
	s_addc_u32 s43, s53, 0
	s_add_i32 s52, s79, s54
	global_load_lds_dwordx4 v[170:171], off
	v_lshl_add_u64 v[170:171], s[42:43], 0, v[174:175]
	s_mov_b32 m0, s52
	s_nop 0
	global_load_lds_dwordx4 v[170:171], off
	v_lshl_add_u64 v[170:171], s[42:43], 0, v[178:179]
	s_add_i32 m0, s52, 0x2000
	s_nop 0
	global_load_lds_dwordx4 v[170:171], off
	v_lshl_add_u64 v[170:171], v[230:231], 0, s[12:13]
	s_mov_b32 m0, s59
	s_nop 0
	global_load_lds_dwordx4 v[170:171], off
	v_lshl_add_u64 v[170:171], v[232:233], 0, s[12:13]
	s_mov_b32 m0, s60
	s_nop 0
	global_load_lds_dwordx4 v[170:171], off
	s_waitcnt vmcnt(8)
	s_waitcnt lgkmcnt(0)
	s_barrier
	s_setprio 1
	s_waitcnt lgkmcnt(0)
	v_mfma_f32_16x16x32_bf16 v[64:67], v[134:137], v[166:169], v[64:67]
	v_mfma_f32_16x16x32_bf16 v[60:63], v[142:145], v[166:169], v[60:63]
	v_mfma_f32_16x16x32_bf16 v[48:51], v[134:137], v[204:207], v[48:51]
	v_mfma_f32_16x16x32_bf16 v[44:47], v[142:145], v[204:207], v[44:47]
	v_mfma_f32_16x16x32_bf16 v[32:35], v[134:137], v[212:215], v[32:35]
	v_mfma_f32_16x16x32_bf16 v[28:31], v[142:145], v[212:215], v[28:31]
	v_mfma_f32_16x16x32_bf16 v[16:19], v[134:137], v[220:223], v[16:19]
	v_mfma_f32_16x16x32_bf16 v[12:15], v[142:145], v[220:223], v[12:15]
	v_mfma_f32_16x16x32_bf16 v[64:67], v[138:141], v[200:203], v[64:67]
	v_mfma_f32_16x16x32_bf16 v[60:63], v[146:149], v[200:203], v[60:63]
	v_mfma_f32_16x16x32_bf16 v[48:51], v[138:141], v[208:211], v[48:51]
	v_mfma_f32_16x16x32_bf16 v[44:47], v[146:149], v[208:211], v[44:47]
	v_mfma_f32_16x16x32_bf16 v[32:35], v[138:141], v[216:219], v[32:35]
	v_mfma_f32_16x16x32_bf16 v[28:31], v[146:149], v[216:219], v[28:31]
	v_mfma_f32_16x16x32_bf16 v[16:19], v[138:141], v[224:227], v[16:19]
	v_mfma_f32_16x16x32_bf16 v[12:15], v[146:149], v[224:227], v[12:15]
	s_setprio 0
	s_setprio 1
	v_mfma_f32_16x16x32_bf16 v[56:59], v[150:153], v[166:169], v[56:59]
	v_mfma_f32_16x16x32_bf16 v[52:55], v[158:161], v[166:169], v[52:55]
	v_mfma_f32_16x16x32_bf16 v[40:43], v[150:153], v[204:207], v[40:43]
	v_mfma_f32_16x16x32_bf16 v[36:39], v[158:161], v[204:207], v[36:39]
	v_mfma_f32_16x16x32_bf16 v[24:27], v[150:153], v[212:215], v[24:27]
	v_mfma_f32_16x16x32_bf16 v[20:23], v[158:161], v[212:215], v[20:23]
	v_mfma_f32_16x16x32_bf16 v[8:11], v[150:153], v[220:223], v[8:11]
	v_mfma_f32_16x16x32_bf16 v[4:7], v[158:161], v[220:223], v[4:7]
	v_mfma_f32_16x16x32_bf16 v[56:59], v[154:157], v[200:203], v[56:59]
	v_mfma_f32_16x16x32_bf16 v[52:55], v[162:165], v[200:203], v[52:55]
	v_mfma_f32_16x16x32_bf16 v[40:43], v[154:157], v[208:211], v[40:43]
	v_mfma_f32_16x16x32_bf16 v[36:39], v[162:165], v[208:211], v[36:39]
	v_mfma_f32_16x16x32_bf16 v[24:27], v[154:157], v[216:219], v[24:27]
	v_mfma_f32_16x16x32_bf16 v[20:23], v[162:165], v[216:219], v[20:23]
	v_mfma_f32_16x16x32_bf16 v[8:11], v[154:157], v[224:227], v[8:11]
	v_mfma_f32_16x16x32_bf16 v[4:7], v[162:165], v[224:227], v[4:7]
	s_setprio 0
	s_barrier
	s_add_u32 s50, s50, 0x100
	s_addc_u32 s51, s51, 0
	s_add_u32 s48, s48, 0x100
	s_addc_u32 s49, s49, 0
	s_add_u32 s46, s46, 0xffffff00
	s_addc_u32 s47, s47, -1
	v_lshl_add_u64 v[132:133], v[132:133], 0, s[16:17]
	s_cmp_ge_u32 s8, s77
	v_lshl_add_u64 v[2:3], v[2:3], 0, s[16:17]
	s_cbranch_scc0 .LBB0_785
	s_and_b64 vcc, exec, s[34:35]
	s_cbranch_vccz .LBB0_783
	v_mov_b32_e32 v0, v188
	s_nop 0
	v_lshl_add_u64 v[2:3], s[44:45], 0, v[0:1]
	v_add_co_u32_e32 v2, vcc, 0x14000000, v2
	s_nop 1
	v_addc_co_u32_e32 v3, vcc, 0, v3, vcc
	global_load_dwordx4 v[160:163], v[2:3], off
	global_load_dwordx4 v[156:159], v[2:3], off offset:256
	v_add_u32_e32 v2, 0x8000, v0
	v_mov_b32_e32 v3, v1
	v_lshl_add_u64 v[2:3], s[44:45], 0, v[2:3]
	v_add_co_u32_e32 v2, vcc, 0x14000000, v2
	s_nop 1
	v_addc_co_u32_e32 v3, vcc, 0, v3, vcc
	global_load_dwordx4 v[152:155], v[2:3], off
	global_load_dwordx4 v[148:151], v[2:3], off offset:256
	v_add_u32_e32 v2, 0x10000, v0
	v_mov_b32_e32 v3, v1
	v_lshl_add_u64 v[2:3], s[44:45], 0, v[2:3]
	v_add_co_u32_e32 v2, vcc, 0x14000000, v2
	s_nop 1
	v_addc_co_u32_e32 v3, vcc, 0, v3, vcc
	global_load_dwordx4 v[144:147], v[2:3], off
	global_load_dwordx4 v[140:143], v[2:3], off offset:256
	v_add_u32_e32 v2, 0x18000, v0
	v_mov_b32_e32 v3, v1
	v_lshl_add_u64 v[2:3], s[44:45], 0, v[2:3]
	v_add_co_u32_e32 v2, vcc, 0x14000000, v2
	s_nop 1
	v_addc_co_u32_e32 v3, vcc, 0, v3, vcc
	global_load_dwordx4 v[136:139], v[2:3], off
	global_load_dwordx4 v[132:135], v[2:3], off offset:256
	v_add_u32_e32 v244, 0x40000, v0
	v_mov_b32_e32 v245, v1
	v_lshl_add_u64 v[244:245], s[44:45], 0, v[244:245]
	v_add_co_u32_e32 v244, vcc, s65, v244
	s_nop 1
	v_addc_co_u32_e32 v245, vcc, 0, v245, vcc
	global_load_dwordx4 v[200:203], v[244:245], off
	global_load_dwordx4 v[204:207], v[244:245], off offset:256
	v_add_u32_e32 v244, 0x48000, v0
	v_mov_b32_e32 v245, v1
	v_lshl_add_u64 v[244:245], s[44:45], 0, v[244:245]
	v_add_co_u32_e32 v244, vcc, s65, v244
	s_nop 1
	v_addc_co_u32_e32 v245, vcc, 0, v245, vcc
	global_load_dwordx4 v[208:211], v[244:245], off
	global_load_dwordx4 v[212:215], v[244:245], off offset:256
	v_add_u32_e32 v244, 0x50000, v0
	v_mov_b32_e32 v245, v1
	v_lshl_add_u64 v[244:245], s[44:45], 0, v[244:245]
	v_add_co_u32_e32 v244, vcc, s65, v244
	s_nop 1
	v_addc_co_u32_e32 v245, vcc, 0, v245, vcc
	global_load_dwordx4 v[216:219], v[244:245], off
	global_load_dwordx4 v[168:171], v[244:245], off offset:256
	v_add_u32_e32 v244, 0x58000, v0
	v_mov_b32_e32 v245, v1
	v_lshl_add_u64 v[244:245], s[44:45], 0, v[244:245]
	v_add_co_u32_e32 v244, vcc, s65, v244
	s_nop 1
	v_addc_co_u32_e32 v245, vcc, 0, v245, vcc
	global_load_dwordx4 v[164:167], v[244:245], off
	global_load_dwordx4 v[240:243], v[244:245], off offset:256
	s_waitcnt vmcnt(8)
; __device__ __forceinline__ float bflo(unsigned w) { return __uint_as_float(w << 16); }
; __device__ __forceinline__ float bfhi(unsigned w) { return __uint_as_float(w & 0xffff0000u); }
;     __device__ __forceinline__ void mid(f32x4 (&acc)[2][2][4][2], const pg8::Unit& u, int wr, int wc, int fr, int fq) const {
;         const int row0 = u.pm * 256 + wr * 64 + fr, col0 = u.pn * 256 + wc * 32 + 8 * fq;
;         unsigned boff = (unsigned)row0 * 2048u + (unsigned)col0 * 2u; asm volatile("" : "+v"(boff));
; #pragma unroll
;         for (int ai = 0; ai < 2; ++ai) {
;             u32x4 ga[4][2];
; #pragma unroll
;             for (int m = 0; m < 4; ++m) { const bf16_t* rowp = (const bf16_t*)((const char*)PJ + (size_t)(boff + (unsigned)((ai * 128 + m * 16) * 2048)));
; #pragma unroll
;                 for (int bj = 0; bj < 2; ++bj) ga[m][bj] = *(const u32x4*)(rowp + T_GA + bj * 128); }
;             __builtin_amdgcn_sched_barrier(0);
; #pragma unroll
;             for (int m = 0; m < 4; ++m)
; #pragma unroll
;                 for (int bj = 0; bj < 2; ++bj) {
;                     const u32x4 a = ga[m][bj];
;                     acc[ai][bj][m][0] = acc[ai][bj][m][0] * (f32x4){bflo(a.x), bfhi(a.x), bflo(a.y), bfhi(a.y)}; acc[ai][bj][m][1] = acc[ai][bj][m][1] * (f32x4){bflo(a.z), bfhi(a.z), bflo(a.w), bfhi(a.w)};
;                 }
;             asm volatile("" ::: "memory");
	v_lshlrev_b32_e32 v2, 16, v160
	v_and_b32_e32 v3, 0xffff0000, v160
	v_pk_mul_f32 v[128:129], v[128:129], v[2:3]
	v_lshlrev_b32_e32 v2, 16, v162
	v_and_b32_e32 v3, 0xffff0000, v162
	v_pk_mul_f32 v[124:125], v[124:125], v[2:3]
	v_lshlrev_b32_e32 v2, 16, v156
	v_and_b32_e32 v3, 0xffff0000, v156
	v_lshlrev_b32_e32 v156, 16, v157
	v_and_b32_e32 v157, 0xffff0000, v157
	v_pk_mul_f32 v[122:123], v[122:123], v[156:157]
	v_add_u32_e32 v156, 0x40000, v0
	v_mov_b32_e32 v157, v1
	v_lshl_add_u64 v[156:157], s[44:45], 0, v[156:157]
	v_add_co_u32_e32 v156, vcc, s65, v156
	v_lshlrev_b32_e32 v160, 16, v161
	s_nop 0
	v_addc_co_u32_e32 v157, vcc, 0, v157, vcc
	v_add_u32_e32 v156, 0x48000, v0
	v_mov_b32_e32 v157, v1
	v_lshl_add_u64 v[156:157], s[44:45], 0, v[156:157]
	v_add_co_u32_e32 v156, vcc, s65, v156
	v_and_b32_e32 v161, 0xffff0000, v161
	s_nop 0
	v_addc_co_u32_e32 v157, vcc, 0, v157, vcc
	v_add_u32_e32 v156, 0x50000, v0
	v_mov_b32_e32 v157, v1
	v_lshl_add_u64 v[156:157], s[44:45], 0, v[156:157]
	v_add_co_u32_e32 v156, vcc, s65, v156
	v_add_u32_e32 v0, 0x58000, v0
	s_nop 0
	v_addc_co_u32_e32 v157, vcc, 0, v157, vcc
	v_lshl_add_u64 v[156:157], s[44:45], 0, v[0:1]
	v_add_co_u32_e32 v156, vcc, s65, v156
	v_pk_mul_f32 v[130:131], v[130:131], v[160:161]
	v_lshlrev_b32_e32 v160, 16, v163
	v_and_b32_e32 v161, 0xffff0000, v163
	v_addc_co_u32_e32 v157, vcc, 0, v157, vcc
	v_pk_mul_f32 v[126:127], v[126:127], v[160:161]
	v_pk_mul_f32 v[120:121], v[120:121], v[2:3]
	v_lshlrev_b32_e32 v2, 16, v158
	v_and_b32_e32 v3, 0xffff0000, v158
	v_pk_mul_f32 v[116:117], v[116:117], v[2:3]
	v_lshlrev_b32_e32 v2, 16, v152
	v_and_b32_e32 v3, 0xffff0000, v152
	v_pk_mul_f32 v[112:113], v[112:113], v[2:3]
	v_lshlrev_b32_e32 v2, 16, v154
	v_and_b32_e32 v3, 0xffff0000, v154
	v_pk_mul_f32 v[108:109], v[108:109], v[2:3]
	v_lshlrev_b32_e32 v2, 16, v148
	v_and_b32_e32 v3, 0xffff0000, v148
	v_pk_mul_f32 v[104:105], v[104:105], v[2:3]
	v_lshlrev_b32_e32 v2, 16, v150
	v_and_b32_e32 v3, 0xffff0000, v150
	v_pk_mul_f32 v[100:101], v[100:101], v[2:3]
	v_lshlrev_b32_e32 v2, 16, v144
	v_and_b32_e32 v3, 0xffff0000, v144
	v_pk_mul_f32 v[96:97], v[96:97], v[2:3]
	v_lshlrev_b32_e32 v2, 16, v146
	v_and_b32_e32 v3, 0xffff0000, v146
	v_pk_mul_f32 v[92:93], v[92:93], v[2:3]
	v_lshlrev_b32_e32 v2, 16, v140
	v_and_b32_e32 v3, 0xffff0000, v140
	v_pk_mul_f32 v[88:89], v[88:89], v[2:3]
	v_lshlrev_b32_e32 v2, 16, v142
	v_and_b32_e32 v3, 0xffff0000, v142
	v_pk_mul_f32 v[84:85], v[84:85], v[2:3]
	v_lshlrev_b32_e32 v2, 16, v136
	v_and_b32_e32 v3, 0xffff0000, v136
	v_pk_mul_f32 v[80:81], v[80:81], v[2:3]
	v_lshlrev_b32_e32 v2, 16, v138
	v_and_b32_e32 v3, 0xffff0000, v138
	v_lshlrev_b32_e32 v152, 16, v153
	v_and_b32_e32 v153, 0xffff0000, v153
	v_lshlrev_b32_e32 v148, 16, v149
	v_and_b32_e32 v149, 0xffff0000, v149
	v_lshlrev_b32_e32 v144, 16, v145
	v_and_b32_e32 v145, 0xffff0000, v145
	v_lshlrev_b32_e32 v140, 16, v141
	v_and_b32_e32 v141, 0xffff0000, v141
	v_lshlrev_b32_e32 v136, 16, v137
	v_and_b32_e32 v137, 0xffff0000, v137
	v_pk_mul_f32 v[76:77], v[76:77], v[2:3]
	v_lshlrev_b32_e32 v2, 16, v132
	v_and_b32_e32 v3, 0xffff0000, v132
	v_lshlrev_b32_e32 v132, 16, v133
	v_and_b32_e32 v133, 0xffff0000, v133
	v_lshlrev_b32_e32 v156, 16, v159
	v_and_b32_e32 v157, 0xffff0000, v159
	v_pk_mul_f32 v[114:115], v[114:115], v[152:153]
	v_lshlrev_b32_e32 v152, 16, v155
	v_and_b32_e32 v153, 0xffff0000, v155
	v_pk_mul_f32 v[106:107], v[106:107], v[148:149]
	v_lshlrev_b32_e32 v148, 16, v151
	v_and_b32_e32 v149, 0xffff0000, v151
	v_pk_mul_f32 v[98:99], v[98:99], v[144:145]
	v_lshlrev_b32_e32 v144, 16, v147
	v_and_b32_e32 v145, 0xffff0000, v147
	v_pk_mul_f32 v[90:91], v[90:91], v[140:141]
	v_lshlrev_b32_e32 v140, 16, v143
	v_and_b32_e32 v141, 0xffff0000, v143
	v_pk_mul_f32 v[82:83], v[82:83], v[136:137]
	v_lshlrev_b32_e32 v136, 16, v139
	v_and_b32_e32 v137, 0xffff0000, v139
	v_pk_mul_f32 v[74:75], v[74:75], v[132:133]
	v_pk_mul_f32 v[72:73], v[72:73], v[2:3]
	v_lshlrev_b32_e32 v2, 16, v134
	v_and_b32_e32 v3, 0xffff0000, v134
	v_lshlrev_b32_e32 v132, 16, v135
	v_and_b32_e32 v133, 0xffff0000, v135
	v_pk_mul_f32 v[118:119], v[118:119], v[156:157]
	v_pk_mul_f32 v[110:111], v[110:111], v[152:153]
	v_pk_mul_f32 v[102:103], v[102:103], v[148:149]
	v_pk_mul_f32 v[94:95], v[94:95], v[144:145]
	v_pk_mul_f32 v[86:87], v[86:87], v[140:141]
	v_pk_mul_f32 v[78:79], v[78:79], v[136:137]
	v_pk_mul_f32 v[70:71], v[70:71], v[132:133]
	v_pk_mul_f32 v[68:69], v[68:69], v[2:3]
	s_waitcnt vmcnt(7)
; __device__ __forceinline__ float bflo(unsigned w) { return __uint_as_float(w << 16); }
; __device__ __forceinline__ float bfhi(unsigned w) { return __uint_as_float(w & 0xffff0000u); }
;     __device__ __forceinline__ void mid(f32x4 (&acc)[2][2][4][2], const pg8::Unit& u, int wr, int wc, int fr, int fq) const {
;     ...
; #pragma unroll
;             for (int m = 0; m < 4; ++m)
; #pragma unroll
;                 for (int bj = 0; bj < 2; ++bj) {
;                     const u32x4 a = ga[m][bj];
;                     acc[ai][bj][m][0] = acc[ai][bj][m][0] * (f32x4){bflo(a.x), bfhi(a.x), bflo(a.y), bfhi(a.y)}; acc[ai][bj][m][1] = acc[ai][bj][m][1] * (f32x4){bflo(a.z), bfhi(a.z), bflo(a.w), bfhi(a.w)};
;                 }
;             asm volatile("" ::: "memory");
;         }
	v_lshlrev_b32_e32 v2, 16, v200
	v_and_b32_e32 v3, 0xffff0000, v200
	v_lshlrev_b32_e32 v132, 16, v201
	v_and_b32_e32 v133, 0xffff0000, v201
	v_pk_mul_f32 v[66:67], v[66:67], v[132:133]
	v_pk_mul_f32 v[64:65], v[64:65], v[2:3]
	v_lshlrev_b32_e32 v2, 16, v202
	v_and_b32_e32 v3, 0xffff0000, v202
	v_lshlrev_b32_e32 v132, 16, v203
	v_and_b32_e32 v133, 0xffff0000, v203
	v_pk_mul_f32 v[62:63], v[62:63], v[132:133]
	v_pk_mul_f32 v[60:61], v[60:61], v[2:3]
	s_waitcnt vmcnt(6)
	v_lshlrev_b32_e32 v2, 16, v204
	v_and_b32_e32 v3, 0xffff0000, v204
	v_lshlrev_b32_e32 v132, 16, v205
	v_and_b32_e32 v133, 0xffff0000, v205
	v_pk_mul_f32 v[58:59], v[58:59], v[132:133]
	v_pk_mul_f32 v[56:57], v[56:57], v[2:3]
	v_lshlrev_b32_e32 v2, 16, v206
	v_and_b32_e32 v3, 0xffff0000, v206
	v_lshlrev_b32_e32 v132, 16, v207
	v_and_b32_e32 v133, 0xffff0000, v207
	v_pk_mul_f32 v[54:55], v[54:55], v[132:133]
	v_pk_mul_f32 v[52:53], v[52:53], v[2:3]
	s_waitcnt vmcnt(5)
	v_lshlrev_b32_e32 v2, 16, v208
	v_and_b32_e32 v3, 0xffff0000, v208
	v_lshlrev_b32_e32 v132, 16, v209
	v_and_b32_e32 v133, 0xffff0000, v209
	v_pk_mul_f32 v[50:51], v[50:51], v[132:133]
	v_pk_mul_f32 v[48:49], v[48:49], v[2:3]
	v_lshlrev_b32_e32 v2, 16, v210
	v_and_b32_e32 v3, 0xffff0000, v210
	v_lshlrev_b32_e32 v132, 16, v211
	v_and_b32_e32 v133, 0xffff0000, v211
	v_pk_mul_f32 v[46:47], v[46:47], v[132:133]
	v_pk_mul_f32 v[44:45], v[44:45], v[2:3]
	s_waitcnt vmcnt(4)
	v_lshlrev_b32_e32 v2, 16, v212
	v_and_b32_e32 v3, 0xffff0000, v212
	v_lshlrev_b32_e32 v132, 16, v213
	v_and_b32_e32 v133, 0xffff0000, v213
	v_pk_mul_f32 v[42:43], v[42:43], v[132:133]
	v_pk_mul_f32 v[40:41], v[40:41], v[2:3]
	v_lshlrev_b32_e32 v2, 16, v214
	v_and_b32_e32 v3, 0xffff0000, v214
	v_lshlrev_b32_e32 v132, 16, v215
	v_and_b32_e32 v133, 0xffff0000, v215
	v_pk_mul_f32 v[38:39], v[38:39], v[132:133]
	v_pk_mul_f32 v[36:37], v[36:37], v[2:3]
	s_waitcnt vmcnt(3)
	v_lshlrev_b32_e32 v2, 16, v216
	v_and_b32_e32 v3, 0xffff0000, v216
	v_lshlrev_b32_e32 v132, 16, v217
	v_and_b32_e32 v133, 0xffff0000, v217
	v_pk_mul_f32 v[34:35], v[34:35], v[132:133]
	v_pk_mul_f32 v[32:33], v[32:33], v[2:3]
	v_lshlrev_b32_e32 v2, 16, v218
	v_and_b32_e32 v3, 0xffff0000, v218
	v_lshlrev_b32_e32 v132, 16, v219
	v_and_b32_e32 v133, 0xffff0000, v219
	v_pk_mul_f32 v[30:31], v[30:31], v[132:133]
	v_pk_mul_f32 v[28:29], v[28:29], v[2:3]
	s_waitcnt vmcnt(2)
	v_lshlrev_b32_e32 v2, 16, v168
	v_and_b32_e32 v3, 0xffff0000, v168
	v_lshlrev_b32_e32 v132, 16, v169
	v_and_b32_e32 v133, 0xffff0000, v169
	v_pk_mul_f32 v[26:27], v[26:27], v[132:133]
	v_pk_mul_f32 v[24:25], v[24:25], v[2:3]
	v_lshlrev_b32_e32 v2, 16, v170
	v_and_b32_e32 v3, 0xffff0000, v170
	v_lshlrev_b32_e32 v132, 16, v171
	v_and_b32_e32 v133, 0xffff0000, v171
	v_pk_mul_f32 v[22:23], v[22:23], v[132:133]
	v_pk_mul_f32 v[20:21], v[20:21], v[2:3]
	s_waitcnt vmcnt(1)
	v_lshlrev_b32_e32 v2, 16, v164
	v_and_b32_e32 v3, 0xffff0000, v164
	v_lshlrev_b32_e32 v132, 16, v165
	v_and_b32_e32 v133, 0xffff0000, v165
	v_pk_mul_f32 v[18:19], v[18:19], v[132:133]
	v_pk_mul_f32 v[16:17], v[16:17], v[2:3]
	v_lshlrev_b32_e32 v2, 16, v166
	v_and_b32_e32 v3, 0xffff0000, v166
	v_lshlrev_b32_e32 v132, 16, v167
	v_and_b32_e32 v133, 0xffff0000, v167
	v_pk_mul_f32 v[14:15], v[14:15], v[132:133]
	v_pk_mul_f32 v[12:13], v[12:13], v[2:3]
	s_waitcnt vmcnt(0)
	v_lshlrev_b32_e32 v2, 16, v240
	v_and_b32_e32 v3, 0xffff0000, v240
	v_lshlrev_b32_e32 v132, 16, v241
	v_and_b32_e32 v133, 0xffff0000, v241
	v_pk_mul_f32 v[10:11], v[10:11], v[132:133]
	v_pk_mul_f32 v[8:9], v[8:9], v[2:3]
	v_lshlrev_b32_e32 v2, 16, v242
	v_and_b32_e32 v3, 0xffff0000, v242
	v_lshlrev_b32_e32 v132, 16, v243
	v_and_b32_e32 v133, 0xffff0000, v243
	v_pk_mul_f32 v[6:7], v[6:7], v[132:133]
	v_pk_mul_f32 v[4:5], v[4:5], v[2:3]
	s_branch .LBB0_783
